# K-loops: removed the setprio 0/1 pair between the two MFMA blocks of each segment
# speedup vs baseline: 1.0076x; 1.0076x over previous
; #define PG8_STAGE(bufoff, gbase, voff) do { _Pragma("unroll") for (int _i = 0; _i < 2; ++_i) \
;         __builtin_amdgcn_global_load_lds((const unsigned*)((const char*)(gbase) + (voff)[_i]), (PG8_LAS unsigned*)(lds + (bufoff) + ldsw + _i * 8192), 16, 0, 0); } while (0)
; #define PG8_LDA(dst, b, h) do { _Pragma("unroll") for (int m = 0; m < 4; ++m) _Pragma("unroll") for (int k = 0; k < 2; ++k) dst[m][k] = *(const PG8_LAS bf16x8*)(lds + PG8_SA(b, h) + aoff + m * 2048 + k * 1024); } while (0)
; #define PG8_LDB(dst, b, h) do { _Pragma("unroll") for (int n = 0; n < 2; ++n) _Pragma("unroll") for (int k = 0; k < 2; ++k) dst[n][k] = *(const PG8_LAS bf16x8*)(lds + PG8_SB(b, h) + boff + n * 2048 + k * 1024); } while (0)
; #define PG8_MMA(ai, bj, At, Bt) do { __builtin_amdgcn_s_setprio(1); _Pragma("unroll") for (int m = 0; m < 4; ++m) _Pragma("unroll") for (int n = 0; n < 2; ++n) _Pragma("unroll") for (int k = 0; k < 2; ++k) \
;         acc[ai][bj][m][n] = __builtin_amdgcn_mfma_f32_16x16x32_bf16(Bt[n][k], At[m][k], acc[ai][bj][m][n], 0, 0, 0); __builtin_amdgcn_s_setprio(0); } while (0)
; #define PG8_WAIT_V(n) asm volatile("s_waitcnt vmcnt(" #n ")" ::: "memory")
; #define PG8_WAIT_L(n) asm volatile("s_waitcnt lgkmcnt(" #n ")" ::: "memory")
; #define PG8_BAR __builtin_amdgcn_s_barrier()
; template <class Epi, class Sched, bool ALIGN_EPI = false, bool SP2 = false>
; __device__ __forceinline__ void gemm_phase(PG8_LAS unsigned char* lds, const Gemm g, const Sched& S, const Epi& E, const int wid_) {
;     ...
;         for (int t = 0; t < nt; t += 2) {
;             const bool last = (t == nt - 2);
;             const char* a1 = cA + (size_t)(t + 1) * kstep;
;             const char* a2 = last ? nA : cA + (size_t)(t + 2) * kstep; const char* b2 = last ? nB : cB + (size_t)(t + 2) * kstep;
;             const char* a3 = a2 + kstep; const char* b3 = b2 + kstep;
;             if (last && has_next) S.a_ready(nxt);
;             if constexpr (SP2) {
;             PG8_LDB(B0, 0, 0); PG8_LDB(B1, 0, 1); PG8_SCHED; PG8_LDA(At, 0, 0); PG8_STAGE(PG8_SA(1, 1), a1 + hstepA, voffA);
;             PG8_WAIT_V(8); PG8_WAIT_L(0); PG8_BAR; PG8_MMA(0, 0, At, B0); PG8_MMA(0, 1, At, B1); PG8_BAR; PG8_SCHED;
;             PG8_LDA(At, 0, 1); PG8_STAGE(PG8_SB(0, 0), b2, voffB); PG8_STAGE(PG8_SB(0, 1), b2 + hstepB, voffB); PG8_STAGE(PG8_SA(0, 0), a2, voffA);
.LBB0_380:
	s_add_i32 s97, s38, 2
	s_add_u32 s98, s6, 0x80
	s_addc_u32 s39, s7, 0
	s_cmp_eq_u32 s41, s38
	s_cselect_b32 s39, s47, s39
	s_cselect_b32 s38, s46, s98
	s_cselect_b32 s99, s61, s62
	s_cselect_b32 s98, s60, s49
	s_add_i32 vcc_lo, 0, 0x14000
	v_add_u32_e32 v164, s42, v180
	v_add_u32_e32 v176, vcc_lo, v180
	ds_read_b128 v[128:131], v164
	ds_read_b128 v[132:135], v164 offset:1024
	ds_read_b128 v[136:139], v164 offset:2048
	ds_read_b128 v[164:167], v164 offset:3072
	ds_read_b128 v[168:171], v176
	ds_read_b128 v[172:175], v176 offset:1024
	ds_read_b128 v[182:185], v176 offset:2048
	ds_read_b128 v[186:189], v176 offset:3072
	v_lshl_add_u64 v[178:179], s[6:7], 0, v[162:163]
	s_add_i32 m0, s36, 0xc000
	ds_read_b128 v[190:193], v181
	ds_read_b128 v[194:197], v181 offset:1024
	ds_read_b128 v[198:201], v181 offset:2048
	ds_read_b128 v[202:205], v181 offset:3072
	ds_read_b128 v[206:209], v181 offset:4096
	ds_read_b128 v[212:215], v181 offset:5120
	ds_read_b128 v[216:219], v181 offset:6144
	ds_read_b128 v[220:223], v181 offset:7168
	global_load_lds_dwordx4 v[178:179], off
	v_lshl_add_u64 v[178:179], s[6:7], 0, v[160:161]
	s_add_i32 m0, s36, 0xe000
	s_nop 0
	global_load_lds_dwordx4 v[178:179], off
	s_waitcnt vmcnt(8)
	s_waitcnt lgkmcnt(0)
	s_barrier
	s_setprio 1
	s_waitcnt lgkmcnt(0)
	v_mfma_f32_16x16x32_bf16 v[124:127], v[128:131], v[190:193], v[124:127]
	v_mfma_f32_16x16x32_bf16 v[120:123], v[136:139], v[190:193], v[120:123]
	v_mfma_f32_16x16x32_bf16 v[116:119], v[128:131], v[198:201], v[116:119]
	v_mfma_f32_16x16x32_bf16 v[112:115], v[136:139], v[198:201], v[112:115]
	v_mfma_f32_16x16x32_bf16 v[100:103], v[128:131], v[206:209], v[100:103]
	v_mfma_f32_16x16x32_bf16 v[96:99], v[136:139], v[206:209], v[96:99]
	v_mfma_f32_16x16x32_bf16 v[84:87], v[128:131], v[216:219], v[84:87]
	v_mfma_f32_16x16x32_bf16 v[80:83], v[136:139], v[216:219], v[80:83]
	v_mfma_f32_16x16x32_bf16 v[124:127], v[132:135], v[194:197], v[124:127]
	v_mfma_f32_16x16x32_bf16 v[120:123], v[164:167], v[194:197], v[120:123]
	v_mfma_f32_16x16x32_bf16 v[116:119], v[132:135], v[202:205], v[116:119]
	v_mfma_f32_16x16x32_bf16 v[112:115], v[164:167], v[202:205], v[112:115]
	v_mfma_f32_16x16x32_bf16 v[100:103], v[132:135], v[212:215], v[100:103]
	v_mfma_f32_16x16x32_bf16 v[96:99], v[164:167], v[212:215], v[96:99]
	v_mfma_f32_16x16x32_bf16 v[84:87], v[132:135], v[220:223], v[84:87]
	v_mfma_f32_16x16x32_bf16 v[80:83], v[164:167], v[220:223], v[80:83]
	v_mfma_f32_16x16x32_bf16 v[108:111], v[168:171], v[190:193], v[108:111]
	v_mfma_f32_16x16x32_bf16 v[104:107], v[182:185], v[190:193], v[104:107]
	v_mfma_f32_16x16x32_bf16 v[92:95], v[168:171], v[198:201], v[92:95]
	v_mfma_f32_16x16x32_bf16 v[88:91], v[182:185], v[198:201], v[88:91]
	v_mfma_f32_16x16x32_bf16 v[76:79], v[168:171], v[206:209], v[76:79]
	v_mfma_f32_16x16x32_bf16 v[72:75], v[182:185], v[206:209], v[72:75]
	v_mfma_f32_16x16x32_bf16 v[68:71], v[168:171], v[216:219], v[68:71]
	v_mfma_f32_16x16x32_bf16 v[64:67], v[182:185], v[216:219], v[64:67]
	v_mfma_f32_16x16x32_bf16 v[108:111], v[172:175], v[194:197], v[108:111]
	v_mfma_f32_16x16x32_bf16 v[104:107], v[186:189], v[194:197], v[104:107]
	v_mfma_f32_16x16x32_bf16 v[92:95], v[172:175], v[202:205], v[92:95]
	v_mfma_f32_16x16x32_bf16 v[88:91], v[186:189], v[202:205], v[88:91]
	v_mfma_f32_16x16x32_bf16 v[76:79], v[172:175], v[212:215], v[76:79]
	v_mfma_f32_16x16x32_bf16 v[72:75], v[186:189], v[212:215], v[72:75]
	v_mfma_f32_16x16x32_bf16 v[68:71], v[172:175], v[220:223], v[68:71]
	v_mfma_f32_16x16x32_bf16 v[64:67], v[186:189], v[220:223], v[64:67]
	s_setprio 0
	s_barrier
	s_add_i32 vcc_hi, s42, s83
	v_lshl_add_u64 v[178:179], s[98:99], 0, v[142:143]
	s_mov_b32 m0, vcc_hi
	ds_read_b128 v[190:193], v181 offset:16384
	ds_read_b128 v[194:197], v181 offset:17408
	ds_read_b128 v[198:201], v181 offset:18432
	ds_read_b128 v[202:205], v181 offset:19456
	ds_read_b128 v[206:209], v181 offset:20480
	ds_read_b128 v[212:215], v181 offset:21504
	ds_read_b128 v[216:219], v181 offset:22528
	ds_read_b128 v[220:223], v181 offset:23552
	global_load_lds_dwordx4 v[178:179], off
	s_add_i32 m0, vcc_hi, 0x2000
	v_lshl_add_u64 v[224:225], s[98:99], 0, v[146:147]
	s_add_u32 s98, s98, s18
	s_addc_u32 s99, s99, 0
	s_add_i32 vcc_lo, vcc_lo, s83
	global_load_lds_dwordx4 v[224:225], off
	v_lshl_add_u64 v[226:227], s[98:99], 0, v[142:143]
	s_mov_b32 m0, vcc_lo
	v_lshl_add_u64 v[228:229], s[98:99], 0, v[146:147]
	global_load_lds_dwordx4 v[226:227], off
	s_add_i32 m0, vcc_lo, 0x2000
	v_lshl_add_u64 v[230:231], s[38:39], 0, v[140:141]
	global_load_lds_dwordx4 v[228:229], off
	s_mov_b32 m0, s36
	v_lshl_add_u64 v[232:233], s[38:39], 0, v[144:145]
	global_load_lds_dwordx4 v[230:231], off
	s_mov_b32 m0, s10
	s_nop 0
	global_load_lds_dwordx4 v[232:233], off
	s_waitcnt vmcnt(8)
	s_waitcnt lgkmcnt(0)
	s_barrier
; #define PG8_STAGE(bufoff, gbase, voff) do { _Pragma("unroll") for (int _i = 0; _i < 2; ++_i) \
;         __builtin_amdgcn_global_load_lds((const unsigned*)((const char*)(gbase) + (voff)[_i]), (PG8_LAS unsigned*)(lds + (bufoff) + ldsw + _i * 8192), 16, 0, 0); } while (0)
; #define PG8_LDA(dst, b, h) do { _Pragma("unroll") for (int m = 0; m < 4; ++m) _Pragma("unroll") for (int k = 0; k < 2; ++k) dst[m][k] = *(const PG8_LAS bf16x8*)(lds + PG8_SA(b, h) + aoff + m * 2048 + k * 1024); } while (0)
; #define PG8_LDB(dst, b, h) do { _Pragma("unroll") for (int n = 0; n < 2; ++n) _Pragma("unroll") for (int k = 0; k < 2; ++k) dst[n][k] = *(const PG8_LAS bf16x8*)(lds + PG8_SB(b, h) + boff + n * 2048 + k * 1024); } while (0)
; #define PG8_MMA(ai, bj, At, Bt) do { __builtin_amdgcn_s_setprio(1); _Pragma("unroll") for (int m = 0; m < 4; ++m) _Pragma("unroll") for (int n = 0; n < 2; ++n) _Pragma("unroll") for (int k = 0; k < 2; ++k) \
;         acc[ai][bj][m][n] = __builtin_amdgcn_mfma_f32_16x16x32_bf16(Bt[n][k], At[m][k], acc[ai][bj][m][n], 0, 0, 0); __builtin_amdgcn_s_setprio(0); } while (0)
; #define PG8_WAIT_V(n) asm volatile("s_waitcnt vmcnt(" #n ")" ::: "memory")
; #define PG8_WAIT_L(n) asm volatile("s_waitcnt lgkmcnt(" #n ")" ::: "memory")
; #define PG8_BAR __builtin_amdgcn_s_barrier()
; #define PG8_SCHED __builtin_amdgcn_sched_barrier(0)
; template <class Epi, class Sched, bool ALIGN_EPI = false, bool SP2 = false>
; __device__ __forceinline__ void gemm_phase(PG8_LAS unsigned char* lds, const Gemm g, const Sched& S, const Epi& E, const int wid_) {
;     ...
;             PG8_WAIT_V(8); PG8_WAIT_L(0); PG8_BAR; PG8_MMA(1, 0, At, B0); PG8_MMA(1, 1, At, B1); PG8_BAR; PG8_SCHED;
;             PG8_LDB(B0, 1, 0); PG8_LDB(B1, 1, 1); PG8_SCHED; PG8_LDA(At, 1, 0); PG8_STAGE(PG8_SA(0, 1), a2 + hstepA, voffA);
;             PG8_WAIT_V(8); PG8_WAIT_L(0); PG8_BAR; PG8_MMA(0, 0, At, B0); PG8_MMA(0, 1, At, B1); PG8_BAR; PG8_SCHED;
	s_setprio 1
	s_waitcnt lgkmcnt(0)
	v_mfma_f32_16x16x32_bf16 v[60:63], v[128:131], v[190:193], v[60:63]
	v_mfma_f32_16x16x32_bf16 v[56:59], v[136:139], v[190:193], v[56:59]
	v_mfma_f32_16x16x32_bf16 v[52:55], v[128:131], v[198:201], v[52:55]
	v_mfma_f32_16x16x32_bf16 v[48:51], v[136:139], v[198:201], v[48:51]
	v_mfma_f32_16x16x32_bf16 v[36:39], v[128:131], v[206:209], v[36:39]
	v_mfma_f32_16x16x32_bf16 v[32:35], v[136:139], v[206:209], v[32:35]
	v_mfma_f32_16x16x32_bf16 v[20:23], v[128:131], v[216:219], v[20:23]
	v_mfma_f32_16x16x32_bf16 v[16:19], v[136:139], v[216:219], v[16:19]
	v_mfma_f32_16x16x32_bf16 v[60:63], v[132:135], v[194:197], v[60:63]
	v_mfma_f32_16x16x32_bf16 v[56:59], v[164:167], v[194:197], v[56:59]
	v_mfma_f32_16x16x32_bf16 v[52:55], v[132:135], v[202:205], v[52:55]
	v_mfma_f32_16x16x32_bf16 v[48:51], v[164:167], v[202:205], v[48:51]
	v_mfma_f32_16x16x32_bf16 v[36:39], v[132:135], v[212:215], v[36:39]
	v_mfma_f32_16x16x32_bf16 v[32:35], v[164:167], v[212:215], v[32:35]
	v_mfma_f32_16x16x32_bf16 v[20:23], v[132:135], v[220:223], v[20:23]
	v_mfma_f32_16x16x32_bf16 v[16:19], v[164:167], v[220:223], v[16:19]
	v_mfma_f32_16x16x32_bf16 v[44:47], v[168:171], v[190:193], v[44:47]
	v_mfma_f32_16x16x32_bf16 v[40:43], v[182:185], v[190:193], v[40:43]
	v_mfma_f32_16x16x32_bf16 v[28:31], v[168:171], v[198:201], v[28:31]
	v_mfma_f32_16x16x32_bf16 v[24:27], v[182:185], v[198:201], v[24:27]
	v_mfma_f32_16x16x32_bf16 v[12:15], v[168:171], v[206:209], v[12:15]
	v_mfma_f32_16x16x32_bf16 v[8:11], v[182:185], v[206:209], v[8:11]
	v_mfma_f32_16x16x32_bf16 v[4:7], v[168:171], v[216:219], v[4:7]
	v_mfma_f32_16x16x32_bf16 v[0:3], v[182:185], v[216:219], v[0:3]
	v_mfma_f32_16x16x32_bf16 v[44:47], v[172:175], v[194:197], v[44:47]
	v_mfma_f32_16x16x32_bf16 v[40:43], v[186:189], v[194:197], v[40:43]
	v_mfma_f32_16x16x32_bf16 v[28:31], v[172:175], v[202:205], v[28:31]
	v_mfma_f32_16x16x32_bf16 v[24:27], v[186:189], v[202:205], v[24:27]
	v_mfma_f32_16x16x32_bf16 v[12:15], v[172:175], v[212:215], v[12:15]
	v_mfma_f32_16x16x32_bf16 v[8:11], v[186:189], v[212:215], v[8:11]
	v_mfma_f32_16x16x32_bf16 v[4:7], v[172:175], v[220:223], v[4:7]
	v_mfma_f32_16x16x32_bf16 v[0:3], v[186:189], v[220:223], v[0:3]
	s_setprio 0
	s_barrier
	s_add_i32 s98, 0, 0x18000
	s_add_i32 s99, 0, 0x1c000
	v_add_u32_e32 v164, s98, v180
	v_add_u32_e32 v176, s99, v180
	ds_read_b128 v[128:131], v164
	ds_read_b128 v[132:135], v164 offset:1024
	ds_read_b128 v[136:139], v164 offset:2048
	ds_read_b128 v[164:167], v164 offset:3072
	ds_read_b128 v[168:171], v176
	ds_read_b128 v[172:175], v176 offset:1024
	ds_read_b128 v[182:185], v176 offset:2048
	ds_read_b128 v[186:189], v176 offset:3072
	s_add_u32 s38, s38, s88
	s_addc_u32 s39, s39, 0
	s_mov_b32 m0, s11
	v_lshl_add_u64 v[234:235], s[38:39], 0, v[140:141]
	ds_read_b128 v[190:193], v181 offset:32768
	ds_read_b128 v[194:197], v181 offset:33792
	ds_read_b128 v[198:201], v181 offset:34816
	ds_read_b128 v[202:205], v181 offset:35840
	ds_read_b128 v[206:209], v181 offset:36864
	ds_read_b128 v[212:215], v181 offset:37888
	ds_read_b128 v[216:219], v181 offset:38912
	ds_read_b128 v[220:223], v181 offset:39936
	global_load_lds_dwordx4 v[234:235], off
	v_lshl_add_u64 v[234:235], s[38:39], 0, v[144:145]
	s_mov_b32 m0, s55
	s_nop 0
	global_load_lds_dwordx4 v[234:235], off
	s_waitcnt vmcnt(8)
	s_waitcnt lgkmcnt(0)
	s_barrier
	s_setprio 1
	s_waitcnt lgkmcnt(0)
	v_mfma_f32_16x16x32_bf16 v[124:127], v[128:131], v[190:193], v[124:127]
	v_mfma_f32_16x16x32_bf16 v[120:123], v[136:139], v[190:193], v[120:123]
	v_mfma_f32_16x16x32_bf16 v[116:119], v[128:131], v[198:201], v[116:119]
	v_mfma_f32_16x16x32_bf16 v[112:115], v[136:139], v[198:201], v[112:115]
	v_mfma_f32_16x16x32_bf16 v[100:103], v[128:131], v[206:209], v[100:103]
	v_mfma_f32_16x16x32_bf16 v[96:99], v[136:139], v[206:209], v[96:99]
	v_mfma_f32_16x16x32_bf16 v[84:87], v[128:131], v[216:219], v[84:87]
	v_mfma_f32_16x16x32_bf16 v[80:83], v[136:139], v[216:219], v[80:83]
	v_mfma_f32_16x16x32_bf16 v[124:127], v[132:135], v[194:197], v[124:127]
	v_mfma_f32_16x16x32_bf16 v[120:123], v[164:167], v[194:197], v[120:123]
	v_mfma_f32_16x16x32_bf16 v[116:119], v[132:135], v[202:205], v[116:119]
	v_mfma_f32_16x16x32_bf16 v[112:115], v[164:167], v[202:205], v[112:115]
	v_mfma_f32_16x16x32_bf16 v[100:103], v[132:135], v[212:215], v[100:103]
	v_mfma_f32_16x16x32_bf16 v[96:99], v[164:167], v[212:215], v[96:99]
	v_mfma_f32_16x16x32_bf16 v[84:87], v[132:135], v[220:223], v[84:87]
	v_mfma_f32_16x16x32_bf16 v[80:83], v[164:167], v[220:223], v[80:83]
	v_mfma_f32_16x16x32_bf16 v[108:111], v[168:171], v[190:193], v[108:111]
	v_mfma_f32_16x16x32_bf16 v[104:107], v[182:185], v[190:193], v[104:107]
	v_mfma_f32_16x16x32_bf16 v[92:95], v[168:171], v[198:201], v[92:95]
	v_mfma_f32_16x16x32_bf16 v[88:91], v[182:185], v[198:201], v[88:91]
	v_mfma_f32_16x16x32_bf16 v[76:79], v[168:171], v[206:209], v[76:79]
	v_mfma_f32_16x16x32_bf16 v[72:75], v[182:185], v[206:209], v[72:75]
	v_mfma_f32_16x16x32_bf16 v[68:71], v[168:171], v[216:219], v[68:71]
	v_mfma_f32_16x16x32_bf16 v[64:67], v[182:185], v[216:219], v[64:67]
	v_mfma_f32_16x16x32_bf16 v[108:111], v[172:175], v[194:197], v[108:111]
	v_mfma_f32_16x16x32_bf16 v[104:107], v[186:189], v[194:197], v[104:107]
	v_mfma_f32_16x16x32_bf16 v[92:95], v[172:175], v[202:205], v[92:95]
	v_mfma_f32_16x16x32_bf16 v[88:91], v[186:189], v[202:205], v[88:91]
	v_mfma_f32_16x16x32_bf16 v[76:79], v[172:175], v[212:215], v[76:79]
	v_mfma_f32_16x16x32_bf16 v[72:75], v[186:189], v[212:215], v[72:75]
	v_mfma_f32_16x16x32_bf16 v[68:71], v[172:175], v[220:223], v[68:71]
	v_mfma_f32_16x16x32_bf16 v[64:67], v[186:189], v[220:223], v[64:67]
	s_setprio 0
	s_barrier
; #define PG8_STAGE(bufoff, gbase, voff) do { _Pragma("unroll") for (int _i = 0; _i < 2; ++_i) \
;         __builtin_amdgcn_global_load_lds((const unsigned*)((const char*)(gbase) + (voff)[_i]), (PG8_LAS unsigned*)(lds + (bufoff) + ldsw + _i * 8192), 16, 0, 0); } while (0)
; #define PG8_LDA(dst, b, h) do { _Pragma("unroll") for (int m = 0; m < 4; ++m) _Pragma("unroll") for (int k = 0; k < 2; ++k) dst[m][k] = *(const PG8_LAS bf16x8*)(lds + PG8_SA(b, h) + aoff + m * 2048 + k * 1024); } while (0)
; #define PG8_MMA(ai, bj, At, Bt) do { __builtin_amdgcn_s_setprio(1); _Pragma("unroll") for (int m = 0; m < 4; ++m) _Pragma("unroll") for (int n = 0; n < 2; ++n) _Pragma("unroll") for (int k = 0; k < 2; ++k) \
;         acc[ai][bj][m][n] = __builtin_amdgcn_mfma_f32_16x16x32_bf16(Bt[n][k], At[m][k], acc[ai][bj][m][n], 0, 0, 0); __builtin_amdgcn_s_setprio(0); } while (0)
; #define PG8_WAIT_V(n) asm volatile("s_waitcnt vmcnt(" #n ")" ::: "memory")
; #define PG8_WAIT_L(n) asm volatile("s_waitcnt lgkmcnt(" #n ")" ::: "memory")
; #define PG8_BAR __builtin_amdgcn_s_barrier()
; #define PG8_SCHED __builtin_amdgcn_sched_barrier(0)
; template <class Epi, class Sched, bool ALIGN_EPI = false, bool SP2 = false>
; __device__ __forceinline__ void gemm_phase(PG8_LAS unsigned char* lds, const Gemm g, const Sched& S, const Epi& E, const int wid_) {
;     ...
;             PG8_LDA(At, 1, 1); PG8_STAGE(PG8_SB(1, 0), b3, voffB); PG8_STAGE(PG8_SB(1, 1), b3 + hstepB, voffB); PG8_STAGE(PG8_SA(1, 0), a3, voffA);
;             PG8_WAIT_V(8); PG8_WAIT_L(0); PG8_BAR; PG8_MMA(1, 0, At, B0); PG8_MMA(1, 1, At, B1); PG8_BAR; PG8_SCHED;
;     ...
;         if constexpr (ALIGN_EPI) { if (wr == 0) PG8_BAR; }
	s_add_i32 s38, s98, s83
	v_lshl_add_u64 v[178:179], v[178:179], 0, s[66:67]
	s_mov_b32 m0, s38
	ds_read_b128 v[190:193], v181 offset:49152
	ds_read_b128 v[194:197], v181 offset:50176
	ds_read_b128 v[198:201], v181 offset:51200
	ds_read_b128 v[202:205], v181 offset:52224
	ds_read_b128 v[206:209], v181 offset:53248
	ds_read_b128 v[212:215], v181 offset:54272
	ds_read_b128 v[216:219], v181 offset:55296
	ds_read_b128 v[220:223], v181 offset:56320
	global_load_lds_dwordx4 v[178:179], off
	v_lshl_add_u64 v[178:179], v[224:225], 0, s[66:67]
	s_add_i32 m0, s38, 0x2000
	s_add_i32 s38, s99, s83
	global_load_lds_dwordx4 v[178:179], off
	v_lshl_add_u64 v[178:179], v[226:227], 0, s[66:67]
	s_mov_b32 m0, s38
	s_nop 0
	global_load_lds_dwordx4 v[178:179], off
	v_lshl_add_u64 v[178:179], v[228:229], 0, s[66:67]
	s_add_i32 m0, s38, 0x2000
	s_nop 0
	global_load_lds_dwordx4 v[178:179], off
	v_lshl_add_u64 v[178:179], v[230:231], 0, s[66:67]
	s_mov_b32 m0, s33
	s_nop 0
	global_load_lds_dwordx4 v[178:179], off
	v_lshl_add_u64 v[178:179], v[232:233], 0, s[66:67]
	s_mov_b32 m0, s52
	s_nop 0
	global_load_lds_dwordx4 v[178:179], off
	s_waitcnt vmcnt(8)
	s_waitcnt lgkmcnt(0)
	s_barrier
	s_setprio 1
	s_waitcnt lgkmcnt(0)
	v_mfma_f32_16x16x32_bf16 v[60:63], v[128:131], v[190:193], v[60:63]
	v_mfma_f32_16x16x32_bf16 v[56:59], v[136:139], v[190:193], v[56:59]
	v_mfma_f32_16x16x32_bf16 v[52:55], v[128:131], v[198:201], v[52:55]
	v_mfma_f32_16x16x32_bf16 v[48:51], v[136:139], v[198:201], v[48:51]
	v_mfma_f32_16x16x32_bf16 v[36:39], v[128:131], v[206:209], v[36:39]
	v_mfma_f32_16x16x32_bf16 v[32:35], v[136:139], v[206:209], v[32:35]
	v_mfma_f32_16x16x32_bf16 v[20:23], v[128:131], v[216:219], v[20:23]
	v_mfma_f32_16x16x32_bf16 v[16:19], v[136:139], v[216:219], v[16:19]
	v_mfma_f32_16x16x32_bf16 v[60:63], v[132:135], v[194:197], v[60:63]
	v_mfma_f32_16x16x32_bf16 v[56:59], v[164:167], v[194:197], v[56:59]
	v_mfma_f32_16x16x32_bf16 v[52:55], v[132:135], v[202:205], v[52:55]
	v_mfma_f32_16x16x32_bf16 v[48:51], v[164:167], v[202:205], v[48:51]
	v_mfma_f32_16x16x32_bf16 v[36:39], v[132:135], v[212:215], v[36:39]
	v_mfma_f32_16x16x32_bf16 v[32:35], v[164:167], v[212:215], v[32:35]
	v_mfma_f32_16x16x32_bf16 v[20:23], v[132:135], v[220:223], v[20:23]
	v_mfma_f32_16x16x32_bf16 v[16:19], v[164:167], v[220:223], v[16:19]
	v_mfma_f32_16x16x32_bf16 v[44:47], v[168:171], v[190:193], v[44:47]
	v_mfma_f32_16x16x32_bf16 v[40:43], v[182:185], v[190:193], v[40:43]
	v_mfma_f32_16x16x32_bf16 v[28:31], v[168:171], v[198:201], v[28:31]
	v_mfma_f32_16x16x32_bf16 v[24:27], v[182:185], v[198:201], v[24:27]
	v_mfma_f32_16x16x32_bf16 v[12:15], v[168:171], v[206:209], v[12:15]
	v_mfma_f32_16x16x32_bf16 v[8:11], v[182:185], v[206:209], v[8:11]
	v_mfma_f32_16x16x32_bf16 v[4:7], v[168:171], v[216:219], v[4:7]
	v_mfma_f32_16x16x32_bf16 v[0:3], v[182:185], v[216:219], v[0:3]
	v_mfma_f32_16x16x32_bf16 v[44:47], v[172:175], v[194:197], v[44:47]
	v_mfma_f32_16x16x32_bf16 v[40:43], v[186:189], v[194:197], v[40:43]
	v_mfma_f32_16x16x32_bf16 v[28:31], v[172:175], v[202:205], v[28:31]
	v_mfma_f32_16x16x32_bf16 v[24:27], v[186:189], v[202:205], v[24:27]
	v_mfma_f32_16x16x32_bf16 v[12:15], v[172:175], v[212:215], v[12:15]
	v_mfma_f32_16x16x32_bf16 v[8:11], v[186:189], v[212:215], v[8:11]
	v_mfma_f32_16x16x32_bf16 v[4:7], v[172:175], v[220:223], v[4:7]
	v_mfma_f32_16x16x32_bf16 v[0:3], v[186:189], v[220:223], v[0:3]
	s_setprio 0
	s_barrier
	s_add_u32 s49, s49, 0x100
	s_addc_u32 s62, s62, 0
	s_add_u32 s6, s6, 0x100
	s_addc_u32 s7, s7, 0
	s_cmp_ge_u32 s97, s71
	s_mov_b32 s38, s97
	s_cbranch_scc0 .LBB0_380
	s_and_b64 vcc, exec, s[94:95]
	s_cbranch_vccz .LBB0_384
	s_barrier
	v_lshl_add_u32 v164, s48, 8, v153
	s_cmp_lt_i32 s37, 2
	s_mov_b64 s[6:7], -1
	s_cbranch_scc0 .LBB0_385

; #define PG8_STAGE(bufoff, gbase, voff) do { _Pragma("unroll") for (int _i = 0; _i < 2; ++_i) \
;         __builtin_amdgcn_global_load_lds((const unsigned*)((const char*)(gbase) + (voff)[_i]), (PG8_LAS unsigned*)(lds + (bufoff) + ldsw + _i * 8192), 16, 0, 0); } while (0)
; #define PG8_LDA(dst, b, h) do { _Pragma("unroll") for (int m = 0; m < 4; ++m) _Pragma("unroll") for (int k = 0; k < 2; ++k) dst[m][k] = *(const PG8_LAS bf16x8*)(lds + PG8_SA(b, h) + aoff + m * 2048 + k * 1024); } while (0)
; #define PG8_LDB(dst, b, h) do { _Pragma("unroll") for (int n = 0; n < 2; ++n) _Pragma("unroll") for (int k = 0; k < 2; ++k) dst[n][k] = *(const PG8_LAS bf16x8*)(lds + PG8_SB(b, h) + boff + n * 2048 + k * 1024); } while (0)
; #define PG8_MMA(ai, bj, At, Bt) do { __builtin_amdgcn_s_setprio(1); _Pragma("unroll") for (int m = 0; m < 4; ++m) _Pragma("unroll") for (int n = 0; n < 2; ++n) _Pragma("unroll") for (int k = 0; k < 2; ++k) \
;         acc[ai][bj][m][n] = __builtin_amdgcn_mfma_f32_16x16x32_bf16(Bt[n][k], At[m][k], acc[ai][bj][m][n], 0, 0, 0); __builtin_amdgcn_s_setprio(0); } while (0)
; #define PG8_WAIT_V(n) asm volatile("s_waitcnt vmcnt(" #n ")" ::: "memory")
; #define PG8_WAIT_L(n) asm volatile("s_waitcnt lgkmcnt(" #n ")" ::: "memory")
; #define PG8_BAR __builtin_amdgcn_s_barrier()
; template <class Epi, class Sched, bool ALIGN_EPI = false, bool SP2 = false>
; __device__ __forceinline__ void gemm_phase(PG8_LAS unsigned char* lds, const Gemm g, const Sched& S, const Epi& E, const int wid_) {
;     ...
;         for (int t = 0; t < nt; t += 2) {
;             const bool last = (t == nt - 2);
;             const char* a1 = cA + (size_t)(t + 1) * kstep;
;             const char* a2 = last ? nA : cA + (size_t)(t + 2) * kstep; const char* b2 = last ? nB : cB + (size_t)(t + 2) * kstep;
;             const char* a3 = a2 + kstep; const char* b3 = b2 + kstep;
;             if (last && has_next) S.a_ready(nxt);
;             if constexpr (SP2) {
;             PG8_LDB(B0, 0, 0); PG8_LDB(B1, 0, 1); PG8_SCHED; PG8_LDA(At, 0, 0); PG8_STAGE(PG8_SA(1, 1), a1 + hstepA, voffA);
;             PG8_WAIT_V(8); PG8_WAIT_L(0); PG8_BAR; PG8_MMA(0, 0, At, B0); PG8_MMA(0, 1, At, B1); PG8_BAR; PG8_SCHED;
;             PG8_LDA(At, 0, 1); PG8_STAGE(PG8_SB(0, 0), b2, voffB); PG8_STAGE(PG8_SB(0, 1), b2 + hstepB, voffB); PG8_STAGE(PG8_SA(0, 0), a2, voffA);
.LBB0_614:
	s_add_i32 s38, s8, 2
	s_add_u32 s39, s6, 0x80
	s_addc_u32 s9, s7, 0
	s_cmp_eq_u32 s80, s8
	s_cselect_b32 s9, s73, s9
	s_cselect_b32 s8, s72, s39
	s_cselect_b32 s87, s75, s76
	s_cselect_b32 s86, s74, s11
	s_add_i32 s39, 0, 0x14000
	v_add_u32_e32 v132, s42, v246
	v_add_u32_e32 v156, s39, v246
	ds_read_b128 v[104:107], v132
	ds_read_b128 v[112:115], v132 offset:1024
	ds_read_b128 v[124:127], v132 offset:2048
	ds_read_b128 v[132:135], v132 offset:3072
	ds_read_b128 v[144:147], v156
	ds_read_b128 v[148:151], v156 offset:1024
	ds_read_b128 v[152:155], v156 offset:2048
	ds_read_b128 v[156:159], v156 offset:3072
	v_lshl_add_u64 v[194:195], s[6:7], 0, v[216:217]
	s_add_i32 m0, s41, 0xc000
	ds_read_b128 v[160:163], v247
	ds_read_b128 v[164:167], v247 offset:1024
	ds_read_b128 v[168:171], v247 offset:2048
	ds_read_b128 v[172:175], v247 offset:3072
	ds_read_b128 v[178:181], v247 offset:4096
	ds_read_b128 v[182:185], v247 offset:5120
	ds_read_b128 v[186:189], v247 offset:6144
	ds_read_b128 v[190:193], v247 offset:7168
	global_load_lds_dwordx4 v[194:195], off
	v_lshl_add_u64 v[194:195], s[6:7], 0, v[214:215]
	s_add_i32 m0, s41, 0xe000
	s_nop 0
	global_load_lds_dwordx4 v[194:195], off
	s_waitcnt vmcnt(8)
	s_waitcnt lgkmcnt(0)
	s_barrier
	s_setprio 1
	s_waitcnt lgkmcnt(0)
	v_mfma_f32_16x16x32_bf16 v[140:143], v[104:107], v[160:163], v[140:143]
	v_mfma_f32_16x16x32_bf16 v[136:139], v[124:127], v[160:163], v[136:139]
	v_mfma_f32_16x16x32_bf16 v[116:119], v[104:107], v[168:171], v[116:119]
	v_mfma_f32_16x16x32_bf16 v[108:111], v[124:127], v[168:171], v[108:111]
	v_mfma_f32_16x16x32_bf16 v[92:95], v[104:107], v[178:181], v[92:95]
	v_mfma_f32_16x16x32_bf16 v[88:91], v[124:127], v[178:181], v[88:91]
	v_mfma_f32_16x16x32_bf16 v[76:79], v[104:107], v[186:189], v[76:79]
	v_mfma_f32_16x16x32_bf16 v[72:75], v[124:127], v[186:189], v[72:75]
	v_mfma_f32_16x16x32_bf16 v[140:143], v[112:115], v[164:167], v[140:143]
	v_mfma_f32_16x16x32_bf16 v[136:139], v[132:135], v[164:167], v[136:139]
	v_mfma_f32_16x16x32_bf16 v[116:119], v[112:115], v[172:175], v[116:119]
	v_mfma_f32_16x16x32_bf16 v[108:111], v[132:135], v[172:175], v[108:111]
	v_mfma_f32_16x16x32_bf16 v[92:95], v[112:115], v[182:185], v[92:95]
	v_mfma_f32_16x16x32_bf16 v[88:91], v[132:135], v[182:185], v[88:91]
	v_mfma_f32_16x16x32_bf16 v[76:79], v[112:115], v[190:193], v[76:79]
	v_mfma_f32_16x16x32_bf16 v[72:75], v[132:135], v[190:193], v[72:75]
	v_mfma_f32_16x16x32_bf16 v[128:131], v[144:147], v[160:163], v[128:131]
	v_mfma_f32_16x16x32_bf16 v[120:123], v[152:155], v[160:163], v[120:123]
	v_mfma_f32_16x16x32_bf16 v[100:103], v[144:147], v[168:171], v[100:103]
	v_mfma_f32_16x16x32_bf16 v[96:99], v[152:155], v[168:171], v[96:99]
	v_mfma_f32_16x16x32_bf16 v[84:87], v[144:147], v[178:181], v[84:87]
	v_mfma_f32_16x16x32_bf16 v[80:83], v[152:155], v[178:181], v[80:83]
	v_mfma_f32_16x16x32_bf16 v[68:71], v[144:147], v[186:189], v[68:71]
	v_mfma_f32_16x16x32_bf16 v[64:67], v[152:155], v[186:189], v[64:67]
	v_mfma_f32_16x16x32_bf16 v[128:131], v[148:151], v[164:167], v[128:131]
	v_mfma_f32_16x16x32_bf16 v[120:123], v[156:159], v[164:167], v[120:123]
	v_mfma_f32_16x16x32_bf16 v[100:103], v[148:151], v[172:175], v[100:103]
	v_mfma_f32_16x16x32_bf16 v[96:99], v[156:159], v[172:175], v[96:99]
	v_mfma_f32_16x16x32_bf16 v[84:87], v[148:151], v[182:185], v[84:87]
	v_mfma_f32_16x16x32_bf16 v[80:83], v[156:159], v[182:185], v[80:83]
	v_mfma_f32_16x16x32_bf16 v[68:71], v[148:151], v[190:193], v[68:71]
	v_mfma_f32_16x16x32_bf16 v[64:67], v[156:159], v[190:193], v[64:67]
	s_setprio 0
	s_barrier
	s_add_i32 s85, s42, s33
	v_lshl_add_u64 v[194:195], s[86:87], 0, v[176:177]
	s_mov_b32 m0, s85
	ds_read_b128 v[160:163], v247 offset:16384
	ds_read_b128 v[164:167], v247 offset:17408
	ds_read_b128 v[168:171], v247 offset:18432
	ds_read_b128 v[172:175], v247 offset:19456
	ds_read_b128 v[178:181], v247 offset:20480
	ds_read_b128 v[182:185], v247 offset:21504
	ds_read_b128 v[186:189], v247 offset:22528
	ds_read_b128 v[190:193], v247 offset:23552
	global_load_lds_dwordx4 v[194:195], off
	s_add_i32 m0, s85, 0x2000
	v_lshl_add_u64 v[196:197], s[86:87], 0, v[202:203]
	s_add_u32 s86, s86, s22
	s_addc_u32 s87, s87, 0
	s_add_i32 s39, s39, s33
	global_load_lds_dwordx4 v[196:197], off
	v_lshl_add_u64 v[198:199], s[86:87], 0, v[176:177]
	s_mov_b32 m0, s39
	v_lshl_add_u64 v[200:201], s[86:87], 0, v[202:203]
	global_load_lds_dwordx4 v[198:199], off
	s_add_i32 m0, s39, 0x2000
	v_lshl_add_u64 v[218:219], s[8:9], 0, v[206:207]
	global_load_lds_dwordx4 v[200:201], off
	s_mov_b32 m0, s41
	v_lshl_add_u64 v[220:221], s[8:9], 0, v[204:205]
	global_load_lds_dwordx4 v[218:219], off
	s_mov_b32 m0, s43
	s_nop 0
	global_load_lds_dwordx4 v[220:221], off
	s_waitcnt vmcnt(8)
	s_waitcnt lgkmcnt(0)
	s_barrier
; #define PG8_STAGE(bufoff, gbase, voff) do { _Pragma("unroll") for (int _i = 0; _i < 2; ++_i) \
;         __builtin_amdgcn_global_load_lds((const unsigned*)((const char*)(gbase) + (voff)[_i]), (PG8_LAS unsigned*)(lds + (bufoff) + ldsw + _i * 8192), 16, 0, 0); } while (0)
; #define PG8_LDA(dst, b, h) do { _Pragma("unroll") for (int m = 0; m < 4; ++m) _Pragma("unroll") for (int k = 0; k < 2; ++k) dst[m][k] = *(const PG8_LAS bf16x8*)(lds + PG8_SA(b, h) + aoff + m * 2048 + k * 1024); } while (0)
; #define PG8_LDB(dst, b, h) do { _Pragma("unroll") for (int n = 0; n < 2; ++n) _Pragma("unroll") for (int k = 0; k < 2; ++k) dst[n][k] = *(const PG8_LAS bf16x8*)(lds + PG8_SB(b, h) + boff + n * 2048 + k * 1024); } while (0)
; #define PG8_MMA(ai, bj, At, Bt) do { __builtin_amdgcn_s_setprio(1); _Pragma("unroll") for (int m = 0; m < 4; ++m) _Pragma("unroll") for (int n = 0; n < 2; ++n) _Pragma("unroll") for (int k = 0; k < 2; ++k) \
;         acc[ai][bj][m][n] = __builtin_amdgcn_mfma_f32_16x16x32_bf16(Bt[n][k], At[m][k], acc[ai][bj][m][n], 0, 0, 0); __builtin_amdgcn_s_setprio(0); } while (0)
; #define PG8_WAIT_V(n) asm volatile("s_waitcnt vmcnt(" #n ")" ::: "memory")
; #define PG8_WAIT_L(n) asm volatile("s_waitcnt lgkmcnt(" #n ")" ::: "memory")
; #define PG8_BAR __builtin_amdgcn_s_barrier()
; #define PG8_SCHED __builtin_amdgcn_sched_barrier(0)
; template <class Epi, class Sched, bool ALIGN_EPI = false, bool SP2 = false>
; __device__ __forceinline__ void gemm_phase(PG8_LAS unsigned char* lds, const Gemm g, const Sched& S, const Epi& E, const int wid_) {
;     ...
;             PG8_WAIT_V(8); PG8_WAIT_L(0); PG8_BAR; PG8_MMA(1, 0, At, B0); PG8_MMA(1, 1, At, B1); PG8_BAR; PG8_SCHED;
;             PG8_LDB(B0, 1, 0); PG8_LDB(B1, 1, 1); PG8_SCHED; PG8_LDA(At, 1, 0); PG8_STAGE(PG8_SA(0, 1), a2 + hstepA, voffA);
;             PG8_WAIT_V(8); PG8_WAIT_L(0); PG8_BAR; PG8_MMA(0, 0, At, B0); PG8_MMA(0, 1, At, B1); PG8_BAR; PG8_SCHED;
	s_setprio 1
	s_waitcnt lgkmcnt(0)
	v_mfma_f32_16x16x32_bf16 v[60:63], v[104:107], v[160:163], v[60:63]
	v_mfma_f32_16x16x32_bf16 v[56:59], v[124:127], v[160:163], v[56:59]
	v_mfma_f32_16x16x32_bf16 v[44:47], v[104:107], v[168:171], v[44:47]
	v_mfma_f32_16x16x32_bf16 v[40:43], v[124:127], v[168:171], v[40:43]
	v_mfma_f32_16x16x32_bf16 v[28:31], v[104:107], v[178:181], v[28:31]
	v_mfma_f32_16x16x32_bf16 v[24:27], v[124:127], v[178:181], v[24:27]
	v_mfma_f32_16x16x32_bf16 v[12:15], v[104:107], v[186:189], v[12:15]
	v_mfma_f32_16x16x32_bf16 v[8:11], v[124:127], v[186:189], v[8:11]
	v_mfma_f32_16x16x32_bf16 v[60:63], v[112:115], v[164:167], v[60:63]
	v_mfma_f32_16x16x32_bf16 v[56:59], v[132:135], v[164:167], v[56:59]
	v_mfma_f32_16x16x32_bf16 v[44:47], v[112:115], v[172:175], v[44:47]
	v_mfma_f32_16x16x32_bf16 v[40:43], v[132:135], v[172:175], v[40:43]
	v_mfma_f32_16x16x32_bf16 v[28:31], v[112:115], v[182:185], v[28:31]
	v_mfma_f32_16x16x32_bf16 v[24:27], v[132:135], v[182:185], v[24:27]
	v_mfma_f32_16x16x32_bf16 v[12:15], v[112:115], v[190:193], v[12:15]
	v_mfma_f32_16x16x32_bf16 v[8:11], v[132:135], v[190:193], v[8:11]
	v_mfma_f32_16x16x32_bf16 v[52:55], v[144:147], v[160:163], v[52:55]
	v_mfma_f32_16x16x32_bf16 v[48:51], v[152:155], v[160:163], v[48:51]
	v_mfma_f32_16x16x32_bf16 v[36:39], v[144:147], v[168:171], v[36:39]
	v_mfma_f32_16x16x32_bf16 v[32:35], v[152:155], v[168:171], v[32:35]
	v_mfma_f32_16x16x32_bf16 v[20:23], v[144:147], v[178:181], v[20:23]
	v_mfma_f32_16x16x32_bf16 v[16:19], v[152:155], v[178:181], v[16:19]
	v_mfma_f32_16x16x32_bf16 v[4:7], v[144:147], v[186:189], v[4:7]
	v_mfma_f32_16x16x32_bf16 v[0:3], v[152:155], v[186:189], v[0:3]
	v_mfma_f32_16x16x32_bf16 v[52:55], v[148:151], v[164:167], v[52:55]
	v_mfma_f32_16x16x32_bf16 v[48:51], v[156:159], v[164:167], v[48:51]
	v_mfma_f32_16x16x32_bf16 v[36:39], v[148:151], v[172:175], v[36:39]
	v_mfma_f32_16x16x32_bf16 v[32:35], v[156:159], v[172:175], v[32:35]
	v_mfma_f32_16x16x32_bf16 v[20:23], v[148:151], v[182:185], v[20:23]
	v_mfma_f32_16x16x32_bf16 v[16:19], v[156:159], v[182:185], v[16:19]
	v_mfma_f32_16x16x32_bf16 v[4:7], v[148:151], v[190:193], v[4:7]
	v_mfma_f32_16x16x32_bf16 v[0:3], v[156:159], v[190:193], v[0:3]
	s_setprio 0
	s_barrier
	s_add_i32 s39, 0, 0x18000
	s_add_i32 s85, 0, 0x1c000
	v_add_u32_e32 v132, s39, v246
	v_add_u32_e32 v156, s85, v246
	ds_read_b128 v[104:107], v132
	ds_read_b128 v[112:115], v132 offset:1024
	ds_read_b128 v[124:127], v132 offset:2048
	ds_read_b128 v[132:135], v132 offset:3072
	ds_read_b128 v[144:147], v156
	ds_read_b128 v[148:151], v156 offset:1024
	ds_read_b128 v[152:155], v156 offset:2048
	ds_read_b128 v[156:159], v156 offset:3072
	s_add_u32 s8, s8, s22
	s_addc_u32 s9, s9, 0
	s_mov_b32 m0, s46
	v_lshl_add_u64 v[222:223], s[8:9], 0, v[206:207]
	ds_read_b128 v[160:163], v247 offset:32768
	ds_read_b128 v[164:167], v247 offset:33792
	ds_read_b128 v[168:171], v247 offset:34816
	ds_read_b128 v[172:175], v247 offset:35840
	ds_read_b128 v[178:181], v247 offset:36864
	ds_read_b128 v[182:185], v247 offset:37888
	ds_read_b128 v[186:189], v247 offset:38912
	ds_read_b128 v[190:193], v247 offset:39936
	global_load_lds_dwordx4 v[222:223], off
	v_lshl_add_u64 v[222:223], s[8:9], 0, v[204:205]
	s_mov_b32 m0, s47
	s_nop 0
	global_load_lds_dwordx4 v[222:223], off
	s_waitcnt vmcnt(8)
	s_waitcnt lgkmcnt(0)
	s_barrier
	s_setprio 1
	s_waitcnt lgkmcnt(0)
	v_mfma_f32_16x16x32_bf16 v[140:143], v[104:107], v[160:163], v[140:143]
	v_mfma_f32_16x16x32_bf16 v[136:139], v[124:127], v[160:163], v[136:139]
	v_mfma_f32_16x16x32_bf16 v[116:119], v[104:107], v[168:171], v[116:119]
	v_mfma_f32_16x16x32_bf16 v[108:111], v[124:127], v[168:171], v[108:111]
	v_mfma_f32_16x16x32_bf16 v[92:95], v[104:107], v[178:181], v[92:95]
	v_mfma_f32_16x16x32_bf16 v[88:91], v[124:127], v[178:181], v[88:91]
	v_mfma_f32_16x16x32_bf16 v[76:79], v[104:107], v[186:189], v[76:79]
	v_mfma_f32_16x16x32_bf16 v[72:75], v[124:127], v[186:189], v[72:75]
	v_mfma_f32_16x16x32_bf16 v[140:143], v[112:115], v[164:167], v[140:143]
	v_mfma_f32_16x16x32_bf16 v[136:139], v[132:135], v[164:167], v[136:139]
	v_mfma_f32_16x16x32_bf16 v[116:119], v[112:115], v[172:175], v[116:119]
	v_mfma_f32_16x16x32_bf16 v[108:111], v[132:135], v[172:175], v[108:111]
	v_mfma_f32_16x16x32_bf16 v[92:95], v[112:115], v[182:185], v[92:95]
	v_mfma_f32_16x16x32_bf16 v[88:91], v[132:135], v[182:185], v[88:91]
	v_mfma_f32_16x16x32_bf16 v[76:79], v[112:115], v[190:193], v[76:79]
	v_mfma_f32_16x16x32_bf16 v[72:75], v[132:135], v[190:193], v[72:75]
	v_mfma_f32_16x16x32_bf16 v[128:131], v[144:147], v[160:163], v[128:131]
	v_mfma_f32_16x16x32_bf16 v[120:123], v[152:155], v[160:163], v[120:123]
	v_mfma_f32_16x16x32_bf16 v[100:103], v[144:147], v[168:171], v[100:103]
	v_mfma_f32_16x16x32_bf16 v[96:99], v[152:155], v[168:171], v[96:99]
	v_mfma_f32_16x16x32_bf16 v[84:87], v[144:147], v[178:181], v[84:87]
	v_mfma_f32_16x16x32_bf16 v[80:83], v[152:155], v[178:181], v[80:83]
	v_mfma_f32_16x16x32_bf16 v[68:71], v[144:147], v[186:189], v[68:71]
	v_mfma_f32_16x16x32_bf16 v[64:67], v[152:155], v[186:189], v[64:67]
	v_mfma_f32_16x16x32_bf16 v[128:131], v[148:151], v[164:167], v[128:131]
	v_mfma_f32_16x16x32_bf16 v[120:123], v[156:159], v[164:167], v[120:123]
	v_mfma_f32_16x16x32_bf16 v[100:103], v[148:151], v[172:175], v[100:103]
	v_mfma_f32_16x16x32_bf16 v[96:99], v[156:159], v[172:175], v[96:99]
	v_mfma_f32_16x16x32_bf16 v[84:87], v[148:151], v[182:185], v[84:87]
	v_mfma_f32_16x16x32_bf16 v[80:83], v[156:159], v[182:185], v[80:83]
	v_mfma_f32_16x16x32_bf16 v[68:71], v[148:151], v[190:193], v[68:71]
	v_mfma_f32_16x16x32_bf16 v[64:67], v[156:159], v[190:193], v[64:67]
	s_setprio 0
	s_barrier
; #define PG8_STAGE(bufoff, gbase, voff) do { _Pragma("unroll") for (int _i = 0; _i < 2; ++_i) \
;         __builtin_amdgcn_global_load_lds((const unsigned*)((const char*)(gbase) + (voff)[_i]), (PG8_LAS unsigned*)(lds + (bufoff) + ldsw + _i * 8192), 16, 0, 0); } while (0)
; #define PG8_LDA(dst, b, h) do { _Pragma("unroll") for (int m = 0; m < 4; ++m) _Pragma("unroll") for (int k = 0; k < 2; ++k) dst[m][k] = *(const PG8_LAS bf16x8*)(lds + PG8_SA(b, h) + aoff + m * 2048 + k * 1024); } while (0)
; #define PG8_MMA(ai, bj, At, Bt) do { __builtin_amdgcn_s_setprio(1); _Pragma("unroll") for (int m = 0; m < 4; ++m) _Pragma("unroll") for (int n = 0; n < 2; ++n) _Pragma("unroll") for (int k = 0; k < 2; ++k) \
;         acc[ai][bj][m][n] = __builtin_amdgcn_mfma_f32_16x16x32_bf16(Bt[n][k], At[m][k], acc[ai][bj][m][n], 0, 0, 0); __builtin_amdgcn_s_setprio(0); } while (0)
; #define PG8_WAIT_V(n) asm volatile("s_waitcnt vmcnt(" #n ")" ::: "memory")
; #define PG8_WAIT_L(n) asm volatile("s_waitcnt lgkmcnt(" #n ")" ::: "memory")
; #define PG8_BAR __builtin_amdgcn_s_barrier()
; #define PG8_SCHED __builtin_amdgcn_sched_barrier(0)
; template <class Epi, class Sched, bool ALIGN_EPI = false, bool SP2 = false>
; __device__ __forceinline__ void gemm_phase(PG8_LAS unsigned char* lds, const Gemm g, const Sched& S, const Epi& E, const int wid_) {
;     ...
;             PG8_LDA(At, 1, 1); PG8_STAGE(PG8_SB(1, 0), b3, voffB); PG8_STAGE(PG8_SB(1, 1), b3 + hstepB, voffB); PG8_STAGE(PG8_SA(1, 0), a3, voffA);
;             PG8_WAIT_V(8); PG8_WAIT_L(0); PG8_BAR; PG8_MMA(1, 0, At, B0); PG8_MMA(1, 1, At, B1); PG8_BAR; PG8_SCHED;
;     ...
;         if constexpr (ALIGN_EPI) { if (wr == 0) PG8_BAR; }
	s_add_i32 s8, s39, s33
	v_lshl_add_u64 v[194:195], v[194:195], 0, s[66:67]
	s_mov_b32 m0, s8
	ds_read_b128 v[160:163], v247 offset:49152
	ds_read_b128 v[164:167], v247 offset:50176
	ds_read_b128 v[168:171], v247 offset:51200
	ds_read_b128 v[172:175], v247 offset:52224
	ds_read_b128 v[178:181], v247 offset:53248
	ds_read_b128 v[182:185], v247 offset:54272
	ds_read_b128 v[186:189], v247 offset:55296
	ds_read_b128 v[190:193], v247 offset:56320
	global_load_lds_dwordx4 v[194:195], off
	v_lshl_add_u64 v[194:195], v[196:197], 0, s[66:67]
	s_add_i32 m0, s8, 0x2000
	s_add_i32 s8, s85, s33
	global_load_lds_dwordx4 v[194:195], off
	v_lshl_add_u64 v[194:195], v[198:199], 0, s[66:67]
	s_mov_b32 m0, s8
	s_nop 0
	global_load_lds_dwordx4 v[194:195], off
	v_lshl_add_u64 v[194:195], v[200:201], 0, s[66:67]
	s_add_i32 m0, s8, 0x2000
	s_nop 0
	global_load_lds_dwordx4 v[194:195], off
	v_lshl_add_u64 v[194:195], v[218:219], 0, s[66:67]
	s_mov_b32 m0, s68
	s_nop 0
	global_load_lds_dwordx4 v[194:195], off
	v_lshl_add_u64 v[194:195], v[220:221], 0, s[66:67]
	s_mov_b32 m0, s69
	s_nop 0
	global_load_lds_dwordx4 v[194:195], off
	s_waitcnt vmcnt(8)
	s_waitcnt lgkmcnt(0)
	s_barrier
	s_setprio 1
	s_waitcnt lgkmcnt(0)
	v_mfma_f32_16x16x32_bf16 v[60:63], v[104:107], v[160:163], v[60:63]
	v_mfma_f32_16x16x32_bf16 v[56:59], v[124:127], v[160:163], v[56:59]
	v_mfma_f32_16x16x32_bf16 v[44:47], v[104:107], v[168:171], v[44:47]
	v_mfma_f32_16x16x32_bf16 v[40:43], v[124:127], v[168:171], v[40:43]
	v_mfma_f32_16x16x32_bf16 v[28:31], v[104:107], v[178:181], v[28:31]
	v_mfma_f32_16x16x32_bf16 v[24:27], v[124:127], v[178:181], v[24:27]
	v_mfma_f32_16x16x32_bf16 v[12:15], v[104:107], v[186:189], v[12:15]
	v_mfma_f32_16x16x32_bf16 v[8:11], v[124:127], v[186:189], v[8:11]
	v_mfma_f32_16x16x32_bf16 v[60:63], v[112:115], v[164:167], v[60:63]
	v_mfma_f32_16x16x32_bf16 v[56:59], v[132:135], v[164:167], v[56:59]
	v_mfma_f32_16x16x32_bf16 v[44:47], v[112:115], v[172:175], v[44:47]
	v_mfma_f32_16x16x32_bf16 v[40:43], v[132:135], v[172:175], v[40:43]
	v_mfma_f32_16x16x32_bf16 v[28:31], v[112:115], v[182:185], v[28:31]
	v_mfma_f32_16x16x32_bf16 v[24:27], v[132:135], v[182:185], v[24:27]
	v_mfma_f32_16x16x32_bf16 v[12:15], v[112:115], v[190:193], v[12:15]
	v_mfma_f32_16x16x32_bf16 v[8:11], v[132:135], v[190:193], v[8:11]
	v_mfma_f32_16x16x32_bf16 v[52:55], v[144:147], v[160:163], v[52:55]
	v_mfma_f32_16x16x32_bf16 v[48:51], v[152:155], v[160:163], v[48:51]
	v_mfma_f32_16x16x32_bf16 v[36:39], v[144:147], v[168:171], v[36:39]
	v_mfma_f32_16x16x32_bf16 v[32:35], v[152:155], v[168:171], v[32:35]
	v_mfma_f32_16x16x32_bf16 v[20:23], v[144:147], v[178:181], v[20:23]
	v_mfma_f32_16x16x32_bf16 v[16:19], v[152:155], v[178:181], v[16:19]
	v_mfma_f32_16x16x32_bf16 v[4:7], v[144:147], v[186:189], v[4:7]
	v_mfma_f32_16x16x32_bf16 v[0:3], v[152:155], v[186:189], v[0:3]
	v_mfma_f32_16x16x32_bf16 v[52:55], v[148:151], v[164:167], v[52:55]
	v_mfma_f32_16x16x32_bf16 v[48:51], v[156:159], v[164:167], v[48:51]
	v_mfma_f32_16x16x32_bf16 v[36:39], v[148:151], v[172:175], v[36:39]
	v_mfma_f32_16x16x32_bf16 v[32:35], v[156:159], v[172:175], v[32:35]
	v_mfma_f32_16x16x32_bf16 v[20:23], v[148:151], v[182:185], v[20:23]
	v_mfma_f32_16x16x32_bf16 v[16:19], v[156:159], v[182:185], v[16:19]
	v_mfma_f32_16x16x32_bf16 v[4:7], v[148:151], v[190:193], v[4:7]
	v_mfma_f32_16x16x32_bf16 v[0:3], v[156:159], v[190:193], v[0:3]
	s_setprio 0
	s_barrier
	s_add_u32 s11, s11, 0x100
	s_addc_u32 s76, s76, 0
	s_add_u32 s6, s6, 0x100
	s_addc_u32 s7, s7, 0
	s_cmp_ge_u32 s38, s71
	s_mov_b32 s8, s38
	s_cbranch_scc0 .LBB0_614
	s_and_b64 vcc, exec, s[36:37]
	s_cbranch_vccz .LBB0_617
	s_barrier
